# speedup vs baseline: 1.0079x; 1.0072x over previous
; __device__ __forceinline__ unsigned cvt_pk_bf16(float lo, float hi) { unsigned r; asm volatile("v_cvt_pk_bf16_f32 %0, %1, %2" : "=v"(r) : "v"(lo), "v"(hi)); return r; }
; #define LAS __attribute__((address_space(3)))
; __device__ __forceinline__ f32x4 mfma16(bf16x8 a, bf16x8 b, f32x4 c) { return __builtin_amdgcn_mfma_f32_16x16x32_bf16(a, b, c, 0, 0, 0); }
; __device__ __forceinline__ bf16x8 cat44(s16x4 lo, s16x4 hi) { return __builtin_shufflevector(lo, hi, 0, 1, 2, 3, 4, 5, 6, 7); }
; __device__ __forceinline__ s16x4 lds_tr(const LAS bf16_t* p) { return __builtin_bit_cast(s16x4, __builtin_amdgcn_ds_read_tr16_b64_v4i16((LAS v4i16_t*)p)); }
; __device__ __forceinline__ void attn_compute(LAS unsigned char* lds, const AttnJob& J, int tid) {
;     ...
;     float mx = NEG_BIG;
; #pragma unroll
;     for (int t = 1; t < 10; ++t) mx = fmaxf(mx, fmaxf(fmaxf(st[t][0], st[t][1]), fmaxf(st[t][2], st[t][3])));
;     mx = fmaxf(mx, __shfl_xor(mx, 16)); mx = fmaxf(mx, __shfl_xor(mx, 32));
;     if (J.has_sink) mx = fmaxf(mx, J.sink);
;     float den = 0.f;
; #pragma unroll
;     for (int t = 1; t < 10; ++t)
; #pragma unroll
;         for (int j = 0; j < 4; ++j) { const float p = __builtin_amdgcn_exp2f(st[t][j] - mx); st[t][j] = p; den += p; }
;     den += __shfl_xor(den, 16); den += __shfl_xor(den, 32);
;     if (J.has_sink) den += __builtin_amdgcn_exp2f(J.sink - mx);
;     f32x4 o[4];
; #pragma unroll
;     for (int dt = 0; dt < 4; ++dt) o[dt] = (f32x4){0.f, 0.f, 0.f, 0.f};
; #pragma unroll
;     for (int ks = 0; ks < 5; ++ks) {
;         u32x4 pw; pw.x = cvt_pk_bf16(st[2 * ks][0], st[2 * ks][1]); pw.y = cvt_pk_bf16(st[2 * ks][2], st[2 * ks][3]); pw.z = cvt_pk_bf16(st[2 * ks + 1][0], st[2 * ks + 1][1]); pw.w = cvt_pk_bf16(st[2 * ks + 1][2], st[2 * ks + 1][3]);
;         const bf16x8 pb = __builtin_bit_cast(bf16x8, pw);
; #pragma unroll
;         for (int dt = 0; dt < 4; ++dt) { const LAS bf16_t* vp = Vs + (16 * w + 32 * ks + quad * 4 + (l15 >> 2)) * AQP + 16 * dt + 4 * (l15 & 3);
;             const s16x4 lo = lds_tr(vp), hi = lds_tr(vp + 16 * AQP);
;             o[dt] = mfma16(cat44(lo, hi), pb, o[dt]); }
.LBB0_219:
	v_max_f32_e32 v33, v101, v101
	v_max_f32_e32 v34, v100, v100
	v_max_f32_e32 v33, v34, v33
	v_max_f32_e32 v34, v103, v103
	v_max_f32_e32 v35, v102, v102
	v_max_f32_e32 v34, v35, v34
	v_max3_f32 v33, v33, v34, s16
	v_max_f32_e32 v34, v95, v95
	v_max_f32_e32 v35, v94, v94
	v_max_f32_e32 v34, v35, v34
	v_max_f32_e32 v35, v91, v91
	v_max_f32_e32 v104, v90, v90
	v_max_f32_e32 v35, v104, v35
	v_max3_f32 v34, v92, v93, v34
	v_max3_f32 v35, v88, v89, v35
	v_max3_f32 v33, v33, v34, v35
	v_max_f32_e32 v34, v87, v87
	v_max_f32_e32 v35, v86, v86
	v_max_f32_e32 v34, v35, v34
	v_max_f32_e32 v35, v83, v83
	v_max_f32_e32 v104, v82, v82
	v_max_f32_e32 v35, v104, v35
	v_max3_f32 v34, v84, v85, v34
	v_max3_f32 v35, v80, v81, v35
	v_max3_f32 v33, v33, v34, v35
	v_max_f32_e32 v34, v79, v79
	v_max_f32_e32 v35, v78, v78
	v_max_f32_e32 v34, v35, v34
	v_max_f32_e32 v35, v71, v71
	v_max_f32_e32 v104, v70, v70
	v_max_f32_e32 v35, v104, v35
	v_max3_f32 v34, v76, v77, v34
	v_max3_f32 v35, v68, v69, v35
	v_max3_f32 v33, v33, v34, v35
	v_max_f32_e32 v34, v75, v75
	v_max_f32_e32 v35, v74, v74
	v_max_f32_e32 v34, v35, v34
	v_max_f32_e32 v35, v99, v99
	v_max_f32_e32 v104, v98, v98
	v_max_f32_e32 v35, v104, v35
	v_max3_f32 v34, v72, v73, v34
	v_max3_f32 v35, v96, v97, v35
	v_max3_f32 v33, v33, v34, v35
	v_mov_b32_e32 v34, v33
	s_ashr_i32 s35, s34, 31
	s_cmp_lg_u64 s[24:25], 0
	s_waitcnt lgkmcnt(0)
	s_nop 3
	v_permlane16_swap_b32 v34, v33
	s_nop 3
	v_max_f32_e32 v33, v33, v34
	v_mov_b32_e32 v34, v33
	s_nop 3
	v_permlane32_swap_b32 v34, v33
	s_nop 3
	v_max_f32_e32 v33, v33, v34
	v_sub_f32_e32 v35, v101, v33
	v_exp_f32_e32 v101, v35
	v_sub_f32_e32 v35, v102, v33
	v_exp_f32_e32 v102, v35
	v_sub_f32_e32 v35, v103, v33
	v_exp_f32_e32 v103, v35
	v_sub_f32_e32 v35, v92, v33
	v_exp_f32_e32 v92, v35
	v_sub_f32_e32 v35, v93, v33
	v_exp_f32_e32 v93, v35
	v_sub_f32_e32 v35, v94, v33
	v_exp_f32_e32 v110, v35
	v_sub_f32_e32 v35, v95, v33
	v_exp_f32_e32 v111, v35
	v_sub_f32_e32 v35, v88, v33
	v_exp_f32_e32 v113, v35
	v_sub_f32_e32 v35, v89, v33
	v_exp_f32_e32 v119, v35
	v_sub_f32_e32 v35, v90, v33
	v_exp_f32_e32 v164, v35
	v_sub_f32_e32 v35, v91, v33
	v_exp_f32_e32 v165, v35
	v_sub_f32_e32 v35, v84, v33
	v_exp_f32_e32 v84, v35
	v_sub_f32_e32 v35, v85, v33
	v_exp_f32_e32 v85, v35
	v_sub_f32_e32 v35, v86, v33
	v_exp_f32_e32 v86, v35
	v_sub_f32_e32 v35, v87, v33
	v_exp_f32_e32 v87, v35
	v_sub_f32_e32 v35, v80, v33
	v_exp_f32_e32 v166, v35
	v_sub_f32_e32 v35, v81, v33
	v_exp_f32_e32 v167, v35
	v_sub_f32_e32 v35, v82, v33
	v_exp_f32_e32 v186, v35
	v_sub_f32_e32 v35, v83, v33
	v_exp_f32_e32 v187, v35
	v_sub_f32_e32 v35, v76, v33
	v_exp_f32_e32 v76, v35
	v_sub_f32_e32 v35, v77, v33
	v_sub_f32_e32 v34, v100, v33
	v_exp_f32_e32 v77, v35
	v_sub_f32_e32 v35, v78, v33
	v_exp_f32_e32 v100, v34
	v_exp_f32_e32 v78, v35
	v_sub_f32_e32 v35, v79, v33
	v_exp_f32_e32 v79, v35
	v_sub_f32_e32 v35, v68, v33
	v_exp_f32_e32 v80, v35
	v_sub_f32_e32 v35, v69, v33
	v_exp_f32_e32 v81, v35
	v_sub_f32_e32 v35, v70, v33
	v_add_f32_e32 v34, 0, v100
	v_exp_f32_e32 v82, v35
	v_sub_f32_e32 v35, v71, v33
	v_add_f32_e32 v34, v101, v34
	v_exp_f32_e32 v83, v35
	v_sub_f32_e32 v35, v72, v33
	v_sub_f32_e32 v68, v73, v33
	v_sub_f32_e32 v69, v74, v33
	v_sub_f32_e32 v71, v96, v33
	v_sub_f32_e32 v72, v97, v33
	v_sub_f32_e32 v73, v98, v33
	v_sub_f32_e32 v74, v99, v33
	v_cvt_pk_bf16_f32 v88, v32, v32
	v_cvt_pk_bf16_f32 v89, v32, v32
	v_cvt_pk_bf16_f32 v90, v100, v101
	v_cvt_pk_bf16_f32 v91, v102, v103
	ds_read_b64_tr_b16 v[96:97], v152 offset:59904
	ds_read_b64_tr_b16 v[94:95], v152 offset:57600
	ds_read_b64_tr_b16 v[98:99], v152 offset:57632
	ds_read_b64_tr_b16 v[100:101], v152 offset:59936
	v_add_f32_e32 v34, v102, v34
	v_add_f32_e32 v34, v103, v34
	ds_read_b64_tr_b16 v[102:103], v152 offset:57664
	ds_read_b64_tr_b16 v[104:105], v152 offset:59968
	ds_read_b64_tr_b16 v[106:107], v152 offset:57696
	ds_read_b64_tr_b16 v[108:109], v152 offset:60000
	v_add_f32_e32 v34, v92, v34
	v_add_f32_e32 v34, v93, v34
	s_waitcnt lgkmcnt(6)
	v_mfma_f32_16x16x32_bf16 v[94:97], v[94:97], v[88:91], 0
	v_add_f32_e32 v34, v110, v34
	v_add_f32_e32 v34, v111, v34
	v_add_f32_e32 v34, v113, v34
	s_waitcnt lgkmcnt(4)
	v_mfma_f32_16x16x32_bf16 v[98:101], v[98:101], v[88:91], 0
	v_add_f32_e32 v34, v119, v34
	v_add_f32_e32 v34, v164, v34
	v_add_f32_e32 v34, v165, v34
	s_waitcnt lgkmcnt(2)
	v_mfma_f32_16x16x32_bf16 v[102:105], v[102:105], v[88:91], 0
	v_add_f32_e32 v34, v84, v34
	v_add_f32_e32 v34, v85, v34
	v_add_f32_e32 v34, v86, v34
	s_waitcnt lgkmcnt(0)
	v_mfma_f32_16x16x32_bf16 v[88:91], v[106:109], v[88:91], 0
	v_cvt_pk_bf16_f32 v106, v92, v93
	v_cvt_pk_bf16_f32 v107, v110, v111
	v_cvt_pk_bf16_f32 v108, v113, v119
	v_cvt_pk_bf16_f32 v109, v164, v165
	ds_read_b64_tr_b16 v[184:185], v152 offset:64512
	ds_read_b64_tr_b16 v[182:183], v152 offset:62208
	ds_read_b64_tr_b16 v[92:93], v152 offset:62240
	s_waitcnt lgkmcnt(1)
	v_mfma_f32_16x16x32_bf16 v[182:185], v[182:185], v[106:109], v[94:97]
	s_nop 2
	ds_read_b64_tr_b16 v[94:95], v152 offset:64544
	v_add_f32_e32 v34, v87, v34
	v_add_f32_e32 v34, v166, v34
	s_waitcnt lgkmcnt(0)
	v_mfma_f32_16x16x32_bf16 v[92:95], v[92:95], v[106:109], v[98:101]
	ds_read_b64_tr_b16 v[96:97], v152 offset:62272
	s_nop 1
	ds_read_b64_tr_b16 v[98:99], v152 offset:64576
	v_add_f32_e32 v34, v167, v34
	v_add_f32_e32 v34, v186, v34
	s_waitcnt lgkmcnt(0)
	v_mfma_f32_16x16x32_bf16 v[96:99], v[96:99], v[106:109], v[102:105]
	ds_read_b64_tr_b16 v[100:101], v152 offset:62304
	s_nop 1
	ds_read_b64_tr_b16 v[102:103], v152 offset:64608
	v_cvt_pk_bf16_f32 v84, v84, v85
	v_cvt_pk_bf16_f32 v85, v86, v87
	s_waitcnt lgkmcnt(0)
; __device__ __forceinline__ unsigned cvt_pk_bf16(float lo, float hi) { unsigned r; asm volatile("v_cvt_pk_bf16_f32 %0, %1, %2" : "=v"(r) : "v"(lo), "v"(hi)); return r; }
; #define LAS __attribute__((address_space(3)))
; __device__ __forceinline__ f32x4 mfma16(bf16x8 a, bf16x8 b, f32x4 c) { return __builtin_amdgcn_mfma_f32_16x16x32_bf16(a, b, c, 0, 0, 0); }
; __device__ __forceinline__ bf16x8 cat44(s16x4 lo, s16x4 hi) { return __builtin_shufflevector(lo, hi, 0, 1, 2, 3, 4, 5, 6, 7); }
; __device__ __forceinline__ s16x4 lds_tr(const LAS bf16_t* p) { return __builtin_bit_cast(s16x4, __builtin_amdgcn_ds_read_tr16_b64_v4i16((LAS v4i16_t*)p)); }
; __device__ __forceinline__ void attn_compute(LAS unsigned char* lds, const AttnJob& J, int tid) {
;     ...
;     den += __shfl_xor(den, 16); den += __shfl_xor(den, 32);
;     if (J.has_sink) den += __builtin_amdgcn_exp2f(J.sink - mx);
;     f32x4 o[4];
; #pragma unroll
;     for (int dt = 0; dt < 4; ++dt) o[dt] = (f32x4){0.f, 0.f, 0.f, 0.f};
; #pragma unroll
;     for (int ks = 0; ks < 5; ++ks) {
;         u32x4 pw; pw.x = cvt_pk_bf16(st[2 * ks][0], st[2 * ks][1]); pw.y = cvt_pk_bf16(st[2 * ks][2], st[2 * ks][3]); pw.z = cvt_pk_bf16(st[2 * ks + 1][0], st[2 * ks + 1][1]); pw.w = cvt_pk_bf16(st[2 * ks + 1][2], st[2 * ks + 1][3]);
;         const bf16x8 pb = __builtin_bit_cast(bf16x8, pw);
; #pragma unroll
;         for (int dt = 0; dt < 4; ++dt) { const LAS bf16_t* vp = Vs + (16 * w + 32 * ks + quad * 4 + (l15 >> 2)) * AQP + 16 * dt + 4 * (l15 & 3);
;             const s16x4 lo = lds_tr(vp), hi = lds_tr(vp + 16 * AQP);
;             o[dt] = mfma16(cat44(lo, hi), pb, o[dt]); }
;     }
;     const float inv = 1.0f / den;
;     const int tokq = J.r + J.dil * (idxq0 + 16 * w + l15);
;     bf16_t* op = J.out + (size_t)tokq * J.out_ld + J.out_col + quad * 4;
; #pragma unroll
;     for (int dt = 0; dt < 4; ++dt) { u32x2 wv; wv.x = cvt_pk_bf16(o[dt][0] * inv, o[dt][1] * inv); wv.y = cvt_pk_bf16(o[dt][2] * inv, o[dt][3] * inv); *(u32x2*)(op + 16 * dt) = wv; }
;     if (J.lse && quad == 0) J.lse[(size_t)tokq * 6 + J.lse_col] = (mx + __builtin_amdgcn_logf(den)) * 0.6931471805599453f;
	v_mfma_f32_16x16x32_bf16 v[88:91], v[100:103], v[106:109], v[88:91]
	v_cvt_pk_bf16_f32 v86, v166, v167
	v_cvt_pk_bf16_f32 v87, v186, v187
	ds_read_b64_tr_b16 v[102:103], v153 offset:11520
	ds_read_b64_tr_b16 v[100:101], v153 offset:9216
	ds_read_b64_tr_b16 v[104:105], v153 offset:9248
	ds_read_b64_tr_b16 v[106:107], v153 offset:11552
	s_waitcnt lgkmcnt(0)
	v_mfma_f32_16x16x32_bf16 v[92:95], v[104:107], v[84:87], v[92:95]
	ds_read_b64_tr_b16 v[104:105], v153 offset:9280
	ds_read_b64_tr_b16 v[106:107], v153 offset:11584
	v_add_f32_e32 v34, v187, v34
	v_add_f32_e32 v34, v76, v34
	v_add_f32_e32 v34, v77, v34
	v_add_f32_e32 v34, v78, v34
	v_add_f32_e32 v34, v79, v34
	s_waitcnt lgkmcnt(0)
	v_mfma_f32_16x16x32_bf16 v[96:99], v[104:107], v[84:87], v[96:99]
	ds_read_b64_tr_b16 v[104:105], v153 offset:9312
	ds_read_b64_tr_b16 v[106:107], v153 offset:11616
	v_add_f32_e32 v34, v80, v34
	v_exp_f32_e32 v35, v35
	v_add_f32_e32 v34, v81, v34
	v_exp_f32_e32 v68, v68
	v_add_f32_e32 v34, v82, v34
	v_exp_f32_e32 v69, v69
	v_sub_f32_e32 v70, v75, v33
	v_add_f32_e32 v34, v83, v34
	v_exp_f32_e32 v70, v70
	v_add_f32_e32 v34, v35, v34
	v_exp_f32_e32 v71, v71
	v_mfma_f32_16x16x32_bf16 v[100:103], v[100:103], v[84:87], v[182:185]
	v_cvt_pk_bf16_f32 v76, v76, v77
	v_cvt_pk_bf16_f32 v77, v78, v79
	v_cvt_pk_bf16_f32 v78, v80, v81
	s_waitcnt lgkmcnt(0)
	v_mfma_f32_16x16x32_bf16 v[84:87], v[104:107], v[84:87], v[88:91]
	v_cvt_pk_bf16_f32 v79, v82, v83
	ds_read_b64_tr_b16 v[82:83], v153 offset:16128
	ds_read_b64_tr_b16 v[80:81], v153 offset:13824
	s_nop 0
	ds_read_b64_tr_b16 v[88:89], v153 offset:13856
	ds_read_b64_tr_b16 v[90:91], v153 offset:16160
	v_add_f32_e32 v34, v68, v34
	v_exp_f32_e32 v72, v72
	v_add_f32_e32 v34, v69, v34
	v_exp_f32_e32 v73, v73
	v_add_f32_e32 v34, v70, v34
	v_exp_f32_e32 v74, v74
	v_add_f32_e32 v34, v71, v34
	v_add_f32_e32 v34, v72, v34
	v_add_f32_e32 v34, v73, v34
	v_add_f32_e32 v34, v74, v34
	v_mov_b32_e32 v75, v34
	s_waitcnt lgkmcnt(0)
	v_mfma_f32_16x16x32_bf16 v[88:91], v[88:91], v[76:79], v[92:95]
	s_nop 2
	ds_read_b64_tr_b16 v[92:93], v153 offset:13888
	ds_read_b64_tr_b16 v[94:95], v153 offset:16192
	v_mov_b32_e32 v119, v32
	v_permlane16_swap_b32 v75, v34
	s_nop 3
	v_add_f32_e32 v34, v34, v75
	v_mov_b32_e32 v75, v34
	s_nop 3
	v_permlane32_swap_b32 v75, v34
	s_waitcnt lgkmcnt(0)
	v_mfma_f32_16x16x32_bf16 v[92:95], v[92:95], v[76:79], v[96:99]
	s_nop 2
	ds_read_b64_tr_b16 v[96:97], v153 offset:13920
	ds_read_b64_tr_b16 v[98:99], v153 offset:16224
	v_cvt_pk_bf16_f32 v68, v35, v68
	v_cvt_pk_bf16_f32 v69, v69, v70
	v_add_f32_e32 v34, v34, v75
	v_mfma_f32_16x16x32_bf16 v[80:83], v[80:83], v[76:79], v[100:103]
	v_cvt_pk_bf16_f32 v70, v71, v72
	v_cvt_pk_bf16_f32 v71, v73, v74
	v_div_scale_f32 v35, s[16:17], v34, v34, 1.0
	s_waitcnt lgkmcnt(0)
	v_mfma_f32_16x16x32_bf16 v[76:79], v[96:99], v[76:79], v[84:87]
	ds_read_b64_tr_b16 v[74:75], v153 offset:20736
	ds_read_b64_tr_b16 v[72:73], v153 offset:18432
	s_nop 0
	ds_read_b64_tr_b16 v[84:85], v153 offset:18464
	ds_read_b64_tr_b16 v[86:87], v153 offset:20768
	s_movk_i32 s16, 0x300
	s_waitcnt lgkmcnt(2)
	v_mfma_f32_16x16x32_bf16 v[72:75], v[72:75], v[68:71], v[80:83]
	s_waitcnt lgkmcnt(0)
	v_mfma_f32_16x16x32_bf16 v[80:83], v[84:87], v[68:71], v[88:91]
	ds_read_b64_tr_b16 v[84:85], v153 offset:18496
	ds_read_b64_tr_b16 v[86:87], v153 offset:20800
	s_nop 0
	ds_read_b64_tr_b16 v[88:89], v153 offset:18528
	ds_read_b64_tr_b16 v[90:91], v153 offset:20832
	s_waitcnt lgkmcnt(2)
	v_mfma_f32_16x16x32_bf16 v[84:87], v[84:87], v[68:71], v[92:95]
	s_waitcnt lgkmcnt(0)
	v_mfma_f32_16x16x32_bf16 v[68:71], v[88:91], v[68:71], v[76:79]
	s_nop 2
	v_rcp_f32_e32 v76, v35
	s_nop 0
	v_fma_f32 v77, -v35, v76, 1.0
	v_fmac_f32_e32 v76, v77, v76
	v_div_scale_f32 v77, vcc, 1.0, v34, 1.0
	v_mul_f32_e32 v78, v77, v76
	v_fma_f32 v79, -v35, v78, v77
	v_fmac_f32_e32 v78, v79, v76
	v_fma_f32 v35, -v35, v78, v77
	v_div_fmas_f32 v35, v35, v76, v78
	v_div_fixup_f32 v78, v35, v34, 1.0
	v_lshl_add_u32 v35, s52, 7, v149
	v_mul_lo_u32 v35, v35, s58
	v_add_u32_e32 v35, s56, v35
	v_mov_b64_e32 v[76:77], s[26:27]
	v_mad_i64_i32 v[76:77], s[16:17], v35, s16, v[76:77]
	v_mul_f32_e32 v72, v78, v72
	v_mul_f32_e32 v73, v78, v73
	v_lshl_add_u64 v[76:77], s[34:35], 1, v[76:77]
	v_cvt_pk_bf16_f32 v72, v72, v73
	v_mul_f32_e32 v73, v78, v74
	v_lshl_add_u64 v[76:77], v[76:77], 0, v[118:119]
	v_mul_f32_e32 v74, v78, v75
	v_cvt_pk_bf16_f32 v73, v73, v74
	s_waitcnt vmcnt(0)
	v_mov_b32_e32 v123, v220
	v_mov_b32_e32 v61, v221
	v_mov_b32_e32 v121, v222
	v_mov_b32_e32 v63, v223
	v_mov_b32_e32 v127, v224
	v_mov_b32_e32 v65, v225
	v_mov_b32_e32 v125, v226
	v_mov_b32_e32 v67, v227
	v_mov_b32_e32 v122, v228
	v_mov_b32_e32 v60, v229
	v_mov_b32_e32 v120, v230
	v_mov_b32_e32 v62, v231
	v_mov_b32_e32 v126, v232
	v_mov_b32_e32 v64, v233
	v_mov_b32_e32 v124, v234
	v_mov_b32_e32 v66, v235
	global_store_dwordx2 v[76:77], v[72:73], off
	v_mul_f32_e32 v72, v78, v80
	v_mul_f32_e32 v73, v78, v81
	v_cvt_pk_bf16_f32 v72, v72, v73
	v_mul_f32_e32 v73, v78, v82
	v_mul_f32_e32 v74, v78, v83
	v_cvt_pk_bf16_f32 v73, v73, v74
	global_store_dwordx2 v[76:77], v[72:73], off offset:32
	v_mul_f32_e32 v72, v78, v84
	v_mul_f32_e32 v73, v78, v85
	v_cvt_pk_bf16_f32 v72, v72, v73
	v_mul_f32_e32 v73, v78, v86
	v_mul_f32_e32 v68, v78, v68
	v_mul_f32_e32 v69, v78, v69
	s_cselect_b64 s[16:17], -1, 0
	v_mul_f32_e32 v74, v78, v87
	v_cvt_pk_bf16_f32 v73, v73, v74
	global_store_dwordx2 v[76:77], v[72:73], off offset:64
	v_cvt_pk_bf16_f32 v68, v68, v69
	v_mul_f32_e32 v69, v78, v70
	s_and_b64 s[74:75], s[82:83], s[16:17]
	v_mul_f32_e32 v70, v78, v71
	v_cvt_pk_bf16_f32 v69, v69, v70
	global_store_dwordx2 v[76:77], v[68:69], off offset:96
	s_and_saveexec_b64 s[16:17], s[74:75]
	s_cbranch_execz .LBB0_221
	v_log_f32_e32 v68, v34
	s_ashr_i32 s37, s36, 31
	v_mad_i64_i32 v[34:35], s[74:75], v35, 24, s[24:25]
	v_add_f32_e32 v33, v33, v68
	v_mul_f32_e32 v33, 0x3f317218, v33
	v_lshl_add_u64 v[34:35], s[36:37], 2, v[34:35]
	global_store_dword v[34:35], v33, off

; __device__ __forceinline__ unsigned cvt_pk_bf16(float lo, float hi) { unsigned r; asm volatile("v_cvt_pk_bf16_f32 %0, %1, %2" : "=v"(r) : "v"(lo), "v"(hi)); return r; }
; #define LAS __attribute__((address_space(3)))
; __device__ __forceinline__ f32x4 mfma16(bf16x8 a, bf16x8 b, f32x4 c) { return __builtin_amdgcn_mfma_f32_16x16x32_bf16(a, b, c, 0, 0, 0); }
; __device__ __forceinline__ bf16x8 cat44(s16x4 lo, s16x4 hi) { return __builtin_shufflevector(lo, hi, 0, 1, 2, 3, 4, 5, 6, 7); }
; __device__ __forceinline__ s16x4 lds_tr(const LAS bf16_t* p) { return __builtin_bit_cast(s16x4, __builtin_amdgcn_ds_read_tr16_b64_v4i16((LAS v4i16_t*)p)); }
; __device__ __forceinline__ void attn_compute(LAS unsigned char* lds, const AttnJob& J, int tid) {
;     ...
;     float mx = NEG_BIG;
; #pragma unroll
;     for (int t = 1; t < 10; ++t) mx = fmaxf(mx, fmaxf(fmaxf(st[t][0], st[t][1]), fmaxf(st[t][2], st[t][3])));
;     mx = fmaxf(mx, __shfl_xor(mx, 16)); mx = fmaxf(mx, __shfl_xor(mx, 32));
;     if (J.has_sink) mx = fmaxf(mx, J.sink);
;     float den = 0.f;
; #pragma unroll
;     for (int t = 1; t < 10; ++t)
; #pragma unroll
;         for (int j = 0; j < 4; ++j) { const float p = __builtin_amdgcn_exp2f(st[t][j] - mx); st[t][j] = p; den += p; }
;     den += __shfl_xor(den, 16); den += __shfl_xor(den, 32);
;     if (J.has_sink) den += __builtin_amdgcn_exp2f(J.sink - mx);
;     f32x4 o[4];
; #pragma unroll
;     for (int dt = 0; dt < 4; ++dt) o[dt] = (f32x4){0.f, 0.f, 0.f, 0.f};
; #pragma unroll
;     for (int ks = 0; ks < 5; ++ks) {
;         u32x4 pw; pw.x = cvt_pk_bf16(st[2 * ks][0], st[2 * ks][1]); pw.y = cvt_pk_bf16(st[2 * ks][2], st[2 * ks][3]); pw.z = cvt_pk_bf16(st[2 * ks + 1][0], st[2 * ks + 1][1]); pw.w = cvt_pk_bf16(st[2 * ks + 1][2], st[2 * ks + 1][3]);
;         const bf16x8 pb = __builtin_bit_cast(bf16x8, pw);
; #pragma unroll
;         for (int dt = 0; dt < 4; ++dt) { const LAS bf16_t* vp = Vs + (16 * w + 32 * ks + quad * 4 + (l15 >> 2)) * AQP + 16 * dt + 4 * (l15 & 3);
;             const s16x4 lo = lds_tr(vp), hi = lds_tr(vp + 16 * AQP);
;             o[dt] = mfma16(cat44(lo, hi), pb, o[dt]); }
.LBB0_269:
	v_max_f32_e32 v34, v101, v101
	v_max_f32_e32 v35, v100, v100
	v_max_f32_e32 v34, v35, v34
	v_max_f32_e32 v35, v103, v103
	v_max_f32_e32 v104, v102, v102
	v_max_f32_e32 v35, v104, v35
	v_max3_f32 v34, v34, v35, s25
	v_max_f32_e32 v35, v99, v99
	v_max_f32_e32 v104, v98, v98
	v_max_f32_e32 v35, v104, v35
	v_max_f32_e32 v104, v91, v91
	v_max_f32_e32 v105, v90, v90
	v_max_f32_e32 v104, v105, v104
	v_max3_f32 v35, v96, v97, v35
	v_max3_f32 v104, v88, v89, v104
	v_max3_f32 v34, v34, v35, v104
	v_max_f32_e32 v35, v87, v87
	v_max_f32_e32 v104, v86, v86
	v_max_f32_e32 v35, v104, v35
	v_max_f32_e32 v104, v83, v83
	v_max_f32_e32 v105, v82, v82
	v_max_f32_e32 v104, v105, v104
	v_max3_f32 v35, v84, v85, v35
	v_max3_f32 v104, v80, v81, v104
	v_max3_f32 v34, v34, v35, v104
	v_max_f32_e32 v35, v79, v79
	v_max_f32_e32 v104, v78, v78
	v_max_f32_e32 v35, v104, v35
	v_max_f32_e32 v104, v71, v71
	v_max_f32_e32 v105, v70, v70
	v_max_f32_e32 v104, v105, v104
	v_max3_f32 v35, v76, v77, v35
	v_max3_f32 v104, v68, v69, v104
	v_max3_f32 v34, v34, v35, v104
	v_max_f32_e32 v35, v75, v75
	v_max_f32_e32 v104, v74, v74
	v_max_f32_e32 v35, v104, v35
	v_max_f32_e32 v104, v95, v95
	v_max_f32_e32 v105, v94, v94
	v_max_f32_e32 v104, v105, v104
	v_max3_f32 v35, v72, v73, v35
	v_max3_f32 v104, v92, v93, v104
	v_max3_f32 v34, v34, v35, v104
	v_mov_b32_e32 v35, v34
	s_ashr_i32 s25, s24, 31
	s_waitcnt lgkmcnt(0)
	s_nop 3
	v_permlane16_swap_b32 v35, v34
	s_nop 3
	v_max_f32_e32 v34, v34, v35
	v_mov_b32_e32 v35, v34
	s_nop 3
	v_permlane32_swap_b32 v35, v34
	s_nop 3
	v_max3_f32 v34, v34, v35, v136
	v_sub_f32_e32 v35, v100, v34
	v_exp_f32_e32 v100, v35
	v_sub_f32_e32 v101, v101, v34
	v_exp_f32_e32 v101, v101
	v_sub_f32_e32 v102, v102, v34
	v_exp_f32_e32 v102, v102
	v_sub_f32_e32 v103, v103, v34
	v_exp_f32_e32 v103, v103
	v_sub_f32_e32 v96, v96, v34
	v_add_f32_e32 v35, 0, v100
	v_exp_f32_e32 v96, v96
	v_sub_f32_e32 v97, v97, v34
	v_add_f32_e32 v35, v101, v35
	v_exp_f32_e32 v97, v97
	v_sub_f32_e32 v98, v98, v34
	v_add_f32_e32 v35, v102, v35
	v_exp_f32_e32 v110, v98
	v_sub_f32_e32 v98, v99, v34
	v_add_f32_e32 v35, v103, v35
	v_exp_f32_e32 v111, v98
	v_sub_f32_e32 v88, v88, v34
	v_add_f32_e32 v35, v96, v35
	v_exp_f32_e32 v113, v88
	v_sub_f32_e32 v88, v89, v34
	v_add_f32_e32 v35, v97, v35
	v_exp_f32_e32 v117, v88
	v_sub_f32_e32 v88, v90, v34
	v_add_f32_e32 v35, v110, v35
	v_exp_f32_e32 v164, v88
	v_sub_f32_e32 v88, v91, v34
	v_add_f32_e32 v35, v111, v35
	v_exp_f32_e32 v165, v88
	v_sub_f32_e32 v84, v84, v34
	v_add_f32_e32 v35, v113, v35
	v_exp_f32_e32 v84, v84
	v_sub_f32_e32 v85, v85, v34
	v_add_f32_e32 v35, v117, v35
	v_exp_f32_e32 v85, v85
	v_sub_f32_e32 v86, v86, v34
	v_add_f32_e32 v35, v164, v35
	v_exp_f32_e32 v86, v86
	v_sub_f32_e32 v87, v87, v34
	v_add_f32_e32 v35, v165, v35
	v_exp_f32_e32 v87, v87
	v_sub_f32_e32 v80, v80, v34
	v_add_f32_e32 v35, v84, v35
	v_exp_f32_e32 v166, v80
	v_sub_f32_e32 v80, v81, v34
	v_add_f32_e32 v35, v85, v35
	v_exp_f32_e32 v167, v80
	v_sub_f32_e32 v80, v82, v34
	v_add_f32_e32 v35, v86, v35
	v_exp_f32_e32 v181, v80
	v_sub_f32_e32 v80, v83, v34
	v_add_f32_e32 v35, v87, v35
	v_exp_f32_e32 v190, v80
	v_sub_f32_e32 v76, v76, v34
	v_add_f32_e32 v35, v166, v35
	v_exp_f32_e32 v76, v76
	v_sub_f32_e32 v77, v77, v34
	v_add_f32_e32 v35, v167, v35
	v_exp_f32_e32 v77, v77
	v_sub_f32_e32 v78, v78, v34
	v_add_f32_e32 v35, v181, v35
	v_exp_f32_e32 v78, v78
	v_sub_f32_e32 v79, v79, v34
	v_add_f32_e32 v35, v190, v35
	v_exp_f32_e32 v79, v79
	v_sub_f32_e32 v68, v68, v34
	v_add_f32_e32 v35, v76, v35
	v_exp_f32_e32 v80, v68
	v_sub_f32_e32 v68, v69, v34
	v_add_f32_e32 v35, v77, v35
	v_exp_f32_e32 v81, v68
	v_sub_f32_e32 v68, v70, v34
	v_add_f32_e32 v35, v78, v35
	v_exp_f32_e32 v82, v68
	v_sub_f32_e32 v68, v71, v34
	v_add_f32_e32 v35, v79, v35
	v_exp_f32_e32 v83, v68
	v_add_f32_e32 v35, v80, v35
	v_add_f32_e32 v35, v81, v35
	v_add_f32_e32 v35, v82, v35
	v_add_f32_e32 v68, v83, v35
	v_sub_f32_e32 v35, v72, v34
	v_exp_f32_e32 v35, v35
	s_nop 0
	v_add_f32_e32 v69, v35, v68
	v_sub_f32_e32 v68, v73, v34
	v_exp_f32_e32 v68, v68
	s_nop 0
	v_add_f32_e32 v70, v68, v69
	v_sub_f32_e32 v69, v74, v34
	v_exp_f32_e32 v69, v69
	s_nop 0
	v_add_f32_e32 v71, v69, v70
	v_sub_f32_e32 v70, v75, v34
	v_exp_f32_e32 v70, v70
	s_nop 0
	v_add_f32_e32 v72, v70, v71
	v_sub_f32_e32 v71, v92, v34
	v_exp_f32_e32 v71, v71
	s_nop 0
	v_add_f32_e32 v73, v71, v72
	v_sub_f32_e32 v72, v93, v34
	v_exp_f32_e32 v72, v72
	s_nop 0
	v_add_f32_e32 v74, v72, v73
	v_sub_f32_e32 v73, v94, v34
	v_exp_f32_e32 v73, v73
	s_nop 0
	v_add_f32_e32 v75, v73, v74
	v_sub_f32_e32 v74, v95, v34
	v_exp_f32_e32 v74, v74
	v_sub_f32_e32 v34, v136, v34
	v_exp_f32_e32 v34, v34
	v_add_f32_e32 v75, v74, v75
	v_mov_b32_e32 v88, v75
	s_waitcnt lgkmcnt(0)
	s_nop 3
	v_permlane16_swap_b32 v88, v75
	s_nop 3
	v_add_f32_e32 v75, v75, v88
	v_mov_b32_e32 v88, v75
	s_nop 3
	v_permlane32_swap_b32 v88, v75
	s_nop 3
	v_add_f32_e32 v75, v75, v88
	v_cvt_pk_bf16_f32 v88, v32, v32
	v_cvt_pk_bf16_f32 v89, v32, v32
	v_cvt_pk_bf16_f32 v90, v100, v101
	v_cvt_pk_bf16_f32 v91, v102, v103
	ds_read_b64_tr_b16 v[94:95], v151 offset:59904
	ds_read_b64_tr_b16 v[92:93], v151 offset:57600
	ds_read_b64_tr_b16 v[98:99], v151 offset:57632
	ds_read_b64_tr_b16 v[100:101], v151 offset:59936
	ds_read_b64_tr_b16 v[102:103], v151 offset:57664
	ds_read_b64_tr_b16 v[104:105], v151 offset:59968
	ds_read_b64_tr_b16 v[106:107], v151 offset:57696
	ds_read_b64_tr_b16 v[108:109], v151 offset:60000
	s_waitcnt lgkmcnt(6)
	v_mfma_f32_16x16x32_bf16 v[92:95], v[92:95], v[88:91], 0
	v_add_f32_e32 v34, v34, v75
	s_waitcnt lgkmcnt(4)
	v_mfma_f32_16x16x32_bf16 v[98:101], v[98:101], v[88:91], 0
	s_waitcnt lgkmcnt(2)
; __device__ __forceinline__ unsigned cvt_pk_bf16(float lo, float hi) { unsigned r; asm volatile("v_cvt_pk_bf16_f32 %0, %1, %2" : "=v"(r) : "v"(lo), "v"(hi)); return r; }
; #define LAS __attribute__((address_space(3)))
; __device__ __forceinline__ void lds_barrier() { asm volatile("s_waitcnt lgkmcnt(0)\n\ts_barrier" ::: "memory"); }
; __device__ __forceinline__ f32x4 mfma16(bf16x8 a, bf16x8 b, f32x4 c) { return __builtin_amdgcn_mfma_f32_16x16x32_bf16(a, b, c, 0, 0, 0); }
; __device__ __forceinline__ bf16x8 cat44(s16x4 lo, s16x4 hi) { return __builtin_shufflevector(lo, hi, 0, 1, 2, 3, 4, 5, 6, 7); }
; __device__ __forceinline__ s16x4 lds_tr(const LAS bf16_t* p) { return __builtin_bit_cast(s16x4, __builtin_amdgcn_ds_read_tr16_b64_v4i16((LAS v4i16_t*)p)); }
; __device__ __forceinline__ void attn_compute(LAS unsigned char* lds, const AttnJob& J, int tid) {
;     ...
;     for (int ks = 0; ks < 5; ++ks) {
;         u32x4 pw; pw.x = cvt_pk_bf16(st[2 * ks][0], st[2 * ks][1]); pw.y = cvt_pk_bf16(st[2 * ks][2], st[2 * ks][3]); pw.z = cvt_pk_bf16(st[2 * ks + 1][0], st[2 * ks + 1][1]); pw.w = cvt_pk_bf16(st[2 * ks + 1][2], st[2 * ks + 1][3]);
;         const bf16x8 pb = __builtin_bit_cast(bf16x8, pw);
; #pragma unroll
;         for (int dt = 0; dt < 4; ++dt) { const LAS bf16_t* vp = Vs + (16 * w + 32 * ks + quad * 4 + (l15 >> 2)) * AQP + 16 * dt + 4 * (l15 & 3);
;             const s16x4 lo = lds_tr(vp), hi = lds_tr(vp + 16 * AQP);
;             o[dt] = mfma16(cat44(lo, hi), pb, o[dt]); }
;     }
;     const float inv = 1.0f / den;
;     const int tokq = J.r + J.dil * (idxq0 + 16 * w + l15);
;     bf16_t* op = J.out + (size_t)tokq * J.out_ld + J.out_col + quad * 4;
; #pragma unroll
;     for (int dt = 0; dt < 4; ++dt) { u32x2 wv; wv.x = cvt_pk_bf16(o[dt][0] * inv, o[dt][1] * inv); wv.y = cvt_pk_bf16(o[dt][2] * inv, o[dt][3] * inv); *(u32x2*)(op + 16 * dt) = wv; }
; __global__ void __launch_bounds__(NTHR, 2) mk_fwd(Args args_unused) {
;     ...
;                         const int un = u + G; const bool hn = un < 2048; AttnJob Jn = J; if (hn) { Jn = make_job_b(un, args.b_sinks + l * 16, ob, ob_ld, ob_c0); if (!(dummy && (PA_VAR & 2))) attn_prefetch(P, PROJ, cAB, sAB, Jn, tq); }
;                         if (!(dummy && (PA_VAR & 1))) attn_compute(lds, J, tq); lds_barrier();
;                         if (!hn) break; J = Jn; u = un; } }
	v_mfma_f32_16x16x32_bf16 v[102:105], v[102:105], v[88:91], 0
	s_waitcnt lgkmcnt(0)
	v_mfma_f32_16x16x32_bf16 v[88:91], v[106:109], v[88:91], 0
	v_cvt_pk_bf16_f32 v106, v96, v97
	v_cvt_pk_bf16_f32 v107, v110, v111
	v_cvt_pk_bf16_f32 v108, v113, v117
	v_cvt_pk_bf16_f32 v109, v164, v165
	ds_read_b64_tr_b16 v[184:185], v151 offset:64512
	ds_read_b64_tr_b16 v[182:183], v151 offset:62208
	ds_read_b64_tr_b16 v[186:187], v151 offset:62240
	ds_read_b64_tr_b16 v[188:189], v151 offset:64544
	s_waitcnt lgkmcnt(2)
	v_mfma_f32_16x16x32_bf16 v[92:95], v[182:185], v[106:109], v[92:95]
	ds_read_b64_tr_b16 v[182:183], v151 offset:62272
	ds_read_b64_tr_b16 v[184:185], v151 offset:64576
	v_mov_b32_e32 v117, v32
	s_waitcnt lgkmcnt(2)
	v_mfma_f32_16x16x32_bf16 v[96:99], v[186:189], v[106:109], v[98:101]
	s_waitcnt lgkmcnt(0)
	v_mfma_f32_16x16x32_bf16 v[100:103], v[182:185], v[106:109], v[102:105]
	ds_read_b64_tr_b16 v[182:183], v151 offset:62304
	ds_read_b64_tr_b16 v[184:185], v151 offset:64608
	v_cvt_pk_bf16_f32 v84, v84, v85
	v_cvt_pk_bf16_f32 v85, v86, v87
	s_waitcnt lgkmcnt(0)
	v_mfma_f32_16x16x32_bf16 v[88:91], v[182:185], v[106:109], v[88:91]
	v_cvt_pk_bf16_f32 v86, v166, v167
	v_cvt_pk_bf16_f32 v87, v181, v190
	ds_read_b64_tr_b16 v[106:107], v152 offset:11520
	ds_read_b64_tr_b16 v[104:105], v152 offset:9216
	ds_read_b64_tr_b16 v[108:109], v152 offset:9248
	s_waitcnt lgkmcnt(1)
	v_mfma_f32_16x16x32_bf16 v[92:95], v[104:107], v[84:87], v[92:95]
	ds_read_b64_tr_b16 v[110:111], v152 offset:11552
	ds_read_b64_tr_b16 v[104:105], v152 offset:9280
	ds_read_b64_tr_b16 v[106:107], v152 offset:11584
	s_waitcnt lgkmcnt(0)
	v_mfma_f32_16x16x32_bf16 v[100:103], v[104:107], v[84:87], v[100:103]
	ds_read_b64_tr_b16 v[104:105], v152 offset:9312
	ds_read_b64_tr_b16 v[106:107], v152 offset:11616
	v_cvt_pk_bf16_f32 v76, v76, v77
	v_cvt_pk_bf16_f32 v77, v78, v79
	v_mfma_f32_16x16x32_bf16 v[96:99], v[108:111], v[84:87], v[96:99]
	v_cvt_pk_bf16_f32 v78, v80, v81
	v_cvt_pk_bf16_f32 v79, v82, v83
	s_waitcnt lgkmcnt(0)
	v_mfma_f32_16x16x32_bf16 v[84:87], v[104:107], v[84:87], v[88:91]
	ds_read_b64_tr_b16 v[82:83], v152 offset:16128
	ds_read_b64_tr_b16 v[80:81], v152 offset:13824
	s_nop 0
	ds_read_b64_tr_b16 v[88:89], v152 offset:13856
	ds_read_b64_tr_b16 v[90:91], v152 offset:16160
	s_waitcnt lgkmcnt(2)
	v_mfma_f32_16x16x32_bf16 v[80:83], v[80:83], v[76:79], v[92:95]
	s_nop 2
	ds_read_b64_tr_b16 v[92:93], v152 offset:13888
	ds_read_b64_tr_b16 v[94:95], v152 offset:16192
	s_waitcnt lgkmcnt(2)
	v_mfma_f32_16x16x32_bf16 v[88:91], v[88:91], v[76:79], v[96:99]
	s_nop 2
	ds_read_b64_tr_b16 v[96:97], v152 offset:13920
	ds_read_b64_tr_b16 v[98:99], v152 offset:16224
	v_cvt_pk_bf16_f32 v68, v35, v68
	v_cvt_pk_bf16_f32 v69, v69, v70
	s_waitcnt lgkmcnt(2)
	v_mfma_f32_16x16x32_bf16 v[92:95], v[92:95], v[76:79], v[100:103]
	v_cvt_pk_bf16_f32 v70, v71, v72
	v_cvt_pk_bf16_f32 v71, v73, v74
	v_div_scale_f32 v35, s[26:27], v34, v34, 1.0
	s_waitcnt lgkmcnt(0)
	v_mfma_f32_16x16x32_bf16 v[76:79], v[96:99], v[76:79], v[84:87]
	ds_read_b64_tr_b16 v[74:75], v152 offset:20736
	ds_read_b64_tr_b16 v[72:73], v152 offset:18432
	s_nop 0
	ds_read_b64_tr_b16 v[84:85], v152 offset:18464
	ds_read_b64_tr_b16 v[86:87], v152 offset:20768
	s_waitcnt lgkmcnt(2)
	v_mfma_f32_16x16x32_bf16 v[72:75], v[72:75], v[68:71], v[80:83]
	s_waitcnt lgkmcnt(0)
	v_mfma_f32_16x16x32_bf16 v[80:83], v[84:87], v[68:71], v[88:91]
	ds_read_b64_tr_b16 v[84:85], v152 offset:18496
	ds_read_b64_tr_b16 v[86:87], v152 offset:20800
	s_nop 0
	ds_read_b64_tr_b16 v[88:89], v152 offset:18528
	ds_read_b64_tr_b16 v[90:91], v152 offset:20832
	s_waitcnt lgkmcnt(2)
	v_mfma_f32_16x16x32_bf16 v[84:87], v[84:87], v[68:71], v[92:95]
	s_waitcnt lgkmcnt(0)
	v_mfma_f32_16x16x32_bf16 v[68:71], v[88:91], v[68:71], v[76:79]
	s_nop 2
	v_rcp_f32_e32 v76, v35
	s_nop 0
	v_fma_f32 v77, -v35, v76, 1.0
	v_fmac_f32_e32 v76, v77, v76
	v_div_scale_f32 v77, vcc, 1.0, v34, 1.0
	v_mul_f32_e32 v78, v77, v76
	v_fma_f32 v79, -v35, v78, v77
	v_fmac_f32_e32 v78, v79, v76
	v_fma_f32 v35, -v35, v78, v77
	v_div_fmas_f32 v35, v35, v76, v78
	v_div_fixup_f32 v76, v35, v34, 1.0
	v_lshl_add_u32 v77, s20, 7, v148
	v_mov_b64_e32 v[34:35], s[40:41]
	v_mad_i64_i32 v[34:35], s[26:27], v77, s23, v[34:35]
	v_mul_f32_e32 v72, v76, v72
	v_mul_f32_e32 v73, v76, v73
	v_lshl_add_u64 v[34:35], s[24:25], 1, v[34:35]
	v_cvt_pk_bf16_f32 v72, v72, v73
	v_mul_f32_e32 v73, v76, v74
	v_lshl_add_u64 v[34:35], v[34:35], 0, v[116:117]
	v_mul_f32_e32 v74, v76, v75
	v_cvt_pk_bf16_f32 v73, v73, v74
	s_waitcnt vmcnt(0)
	v_mul_f32_e32 v33, 0x3fb8aa3b, v236
	v_mov_b32_e32 v60, v220
	v_mov_b32_e32 v120, v221
	v_mov_b32_e32 v62, v222
	v_mov_b32_e32 v118, v223
	v_mov_b32_e32 v64, v224
	v_mov_b32_e32 v124, v225
	v_mov_b32_e32 v66, v226
	v_mov_b32_e32 v122, v227
	v_mov_b32_e32 v61, v228
	v_mov_b32_e32 v121, v229
	v_mov_b32_e32 v63, v230
	v_mov_b32_e32 v119, v231
	v_mov_b32_e32 v65, v232
	v_mov_b32_e32 v125, v233
	v_mov_b32_e32 v67, v234
	v_mov_b32_e32 v123, v235
	global_store_dwordx2 v[34:35], v[72:73], off
	v_mul_f32_e32 v72, v76, v80
	v_mul_f32_e32 v73, v76, v81
	v_cvt_pk_bf16_f32 v72, v72, v73
	v_mul_f32_e32 v73, v76, v82
	v_mul_f32_e32 v74, v76, v83
	v_cvt_pk_bf16_f32 v73, v73, v74
	global_store_dwordx2 v[34:35], v[72:73], off offset:32
	v_mul_f32_e32 v72, v76, v84
	v_mul_f32_e32 v73, v76, v85
	v_cvt_pk_bf16_f32 v72, v72, v73
	v_mul_f32_e32 v73, v76, v86
	v_mul_f32_e32 v68, v76, v68
	v_mul_f32_e32 v69, v76, v69
	v_mul_f32_e32 v74, v76, v87
	v_cvt_pk_bf16_f32 v73, v73, v74
	global_store_dwordx2 v[34:35], v[72:73], off offset:64
	v_cvt_pk_bf16_f32 v68, v68, v69
	v_mul_f32_e32 v69, v76, v70
	v_mul_f32_e32 v70, v76, v71
	v_cvt_pk_bf16_f32 v69, v69, v70
	global_store_dwordx2 v[34:35], v[68:69], off offset:96
	s_waitcnt lgkmcnt(0)
	s_barrier
	s_andn2_b64 vcc, exec, s[30:31]
	s_cbranch_vccnz .LBB0_241
	s_mov_b32 s24, s34
	v_mov_b32_e32 v136, v33
	s_mov_b32 s20, s91
	s_mov_b32 s22, s33
	s_branch .LBB0_241
